# Y products issued before the SA-half update, this sub-chunk's y stores placed under the SA-half MFMAs, two V-half MFMAs ahead of the substitution chain
# speedup vs baseline: 1.0092x; 1.0066x over previous
.Lmy_ck_nz:
	s_mov_b32 s100, 0xe000
	s_cmp_eq_u32 s23, 0
	s_cselect_b32 s100, 0x1c000, s100
	s_mov_b32 s101, 0x12e00
	s_cselect_b32 s101, 0x22100, s101
	s_lshl_b32 s96, s23, 13
	s_add_i32 s97, s96, 0x18000
	s_add_i32 s96, s96, 0xa000
	v_add_u32_e32 v225, s100, v1
	v_add_u32_e32 v236, s100, v0
	v_add_u32_e32 v34, s100, v10
	v_add_u32_e32 v226, s100, v2
	v_add_u32_e32 v227, s100, v3
	v_add_u32_e32 v228, s100, v4
	v_add_u32_e32 v229, s100, v5
	v_add_u32_e32 v237, s100, v6
	v_add_u32_e32 v238, s100, v7
	v_add_u32_e32 v230, s96, v8
	v_add_u32_e32 v239, s96, v9
	v_add_u32_e32 v231, s97, v8
	v_add_u32_e32 v26, s101, v1
	v_add_u32_e32 v27, s101, v0
	v_add_u32_e32 v35, s101, v10
	v_add_u32_e32 v28, s101, v2
	v_add_u32_e32 v29, s101, v3
	v_add_u32_e32 v30, s101, v4
	v_add_u32_e32 v31, s101, v5
	v_add_u32_e32 v32, s101, v6
	v_add_u32_e32 v33, s101, v7
	ds_read_b64 v[80:81], v237
	ds_read_b64 v[82:83], v238
	ds_read_b32 v36, v239
	ds_read_b32 v37, v239 offset:256
	ds_read_b128 v[88:91], v225
	ds_read_b128 v[92:95], v225 offset:1024
	ds_read_b128 v[96:99], v225 offset:2048
	ds_read_b128 v[100:103], v225 offset:3072
	ds_read_b32 v104, v227 offset:4
	ds_read_b32 v105, v227 offset:76
	ds_read_b64 v[106:107], v227 offset:8
	ds_read_b64 v[108:109], v227 offset:40
	ds_read_b32 v126, v229 offset:4
	ds_read_b32 v127, v229 offset:76
	ds_read_b64 v[128:129], v229 offset:8
	ds_read_b64 v[130:131], v229 offset:40
	ds_read_b64 v[110:111], v228
	ds_read_b64 v[112:113], v228 offset:32
	ds_read_b64 v[114:115], v228 offset:64
	ds_read_b64 v[116:117], v228 offset:96
	ds_read_b64 v[118:119], v228 offset:8
	ds_read_b64 v[120:121], v228 offset:40
	ds_read_b64 v[122:123], v228 offset:72
	ds_read_b64 v[124:125], v228 offset:104
	s_waitcnt lgkmcnt(15)
	v_mfma_f32_16x16x4_f32 v[240:243], v80, v36, 0
	v_mfma_f32_16x16x4_f32 v[240:243], v81, v37, v[240:243]
	v_mfma_f32_16x16x4_f32 v[240:243], v88, v208, v[240:243]
	ds_read_b64 v[186:187], v34
	ds_read_b64 v[190:191], v34 offset:1024
	v_mfma_f32_16x16x4_f32 v[244:247], v89, v209, 0
	ds_read_b64 v[194:195], v34 offset:2048
	ds_read_b64 v[198:199], v34 offset:3072
	v_mfma_f32_16x16x4_f32 v[240:243], v90, v210, v[240:243]
	ds_read_b64 v[184:185], v236
	ds_read_b64 v[188:189], v236 offset:1024
	ds_read_b64 v[132:133], v237 offset:9984
	ds_read_b64 v[134:135], v238 offset:9984
	v_mfma_f32_16x16x4_f32 v[244:247], v91, v211, v[244:247]
	ds_read_b64 v[192:193], v236 offset:2048
	ds_read_b64 v[196:197], v236 offset:3072
	ds_read_b32 v38, v239 offset:2048
	ds_read_b32 v39, v239 offset:2304
	v_mfma_f32_16x16x4_f32 v[240:243], v92, v212, v[240:243]
	ds_read_b128 v[140:143], v225 offset:9984
	ds_read_b128 v[144:147], v225 offset:11008
	v_mfma_f32_16x16x4_f32 v[244:247], v93, v213, v[244:247]
	ds_read_b128 v[148:151], v225 offset:12032
	ds_read_b128 v[152:155], v225 offset:13056
	v_mfma_f32_16x16x4_f32 v[240:243], v94, v214, v[240:243]
	ds_read_b32 v156, v227 offset:9988
	ds_read_b32 v157, v227 offset:10060
	v_mfma_f32_16x16x4_f32 v[244:247], v95, v215, v[244:247]
	ds_read_b64 v[158:159], v227 offset:9992
	ds_read_b64 v[160:161], v227 offset:10024
	v_mfma_f32_16x16x4_f32 v[240:243], v96, v216, v[240:243]
	ds_read_b32 v178, v229 offset:9988
	ds_read_b32 v179, v229 offset:10060
	v_mfma_f32_16x16x4_f32 v[244:247], v97, v217, v[244:247]
	ds_read_b64 v[180:181], v229 offset:9992
	ds_read_b64 v[182:183], v229 offset:10024
	v_mfma_f32_16x16x4_f32 v[240:243], v98, v218, v[240:243]
	ds_read_b64 v[162:163], v228 offset:9984
	ds_read_b64 v[164:165], v228 offset:10016
	v_mfma_f32_16x16x4_f32 v[244:247], v99, v219, v[244:247]
	ds_read_b64 v[166:167], v228 offset:10048
	ds_read_b64 v[168:169], v228 offset:10080
	v_mfma_f32_16x16x4_f32 v[240:243], v100, v220, v[240:243]
	ds_read_b64 v[170:171], v228 offset:9992
	ds_read_b64 v[172:173], v228 offset:10024
	v_mfma_f32_16x16x4_f32 v[244:247], v101, v221, v[244:247]
	ds_read_b64 v[174:175], v228 offset:10056
	ds_read_b64 v[176:177], v228 offset:10088
	v_mfma_f32_16x16x4_f32 v[240:243], v102, v222, v[240:243]
	v_mfma_f32_16x16x4_f32 v[244:247], v103, v223, v[244:247]
	s_waitcnt lgkmcnt(15)
	v_mfma_f32_16x16x4_f32 v[208:211], v186, v36, v[208:211]
	v_mfma_f32_16x16x4_f32 v[212:215], v190, v36, v[212:215]
	v_pk_add_f32 v[240:241], v[240:241], v[244:245]
	v_pk_add_f32 v[242:243], v[242:243], v[246:247]
	v_fmac_f32_e32 v241, v104, v240
	v_mfma_f32_16x16x4_f32 v[216:219], v194, v36, v[216:219]
	v_pk_fma_f32 v[242:243], v[106:107], v[240:241], v[242:243] op_sel:[0,0,0] op_sel_hi:[1,0,1]
	v_pk_fma_f32 v[242:243], v[108:109], v[240:241], v[242:243] op_sel:[0,1,0] op_sel_hi:[1,1,1]
	v_fmac_f32_e32 v243, v105, v242
	v_mfma_f32_16x16x4_f32 v[72:75], v132, v38, 0
	ds_bpermute_b32 v204, v232, v240
	ds_bpermute_b32 v205, v232, v241
	ds_bpermute_b32 v206, v232, v242
	v_mfma_f32_16x16x4_f32 v[72:75], v133, v39, v[72:75]
	ds_bpermute_b32 v207, v232, v243
	ds_read_b128 v[88:91], v226
	ds_read_b128 v[92:95], v226 offset:64
	v_mfma_f32_16x16x4_f32 v[220:223], v198, v36, v[220:223]
	ds_read_b128 v[96:99], v226 offset:128
	ds_read_b128 v[100:103], v226 offset:192
	s_waitcnt lgkmcnt(6)
	v_pk_fma_f32 v[240:241], v[110:111], v[204:205], v[240:241] op_sel:[0,0,0] op_sel_hi:[1,0,1]
	v_mfma_f32_16x16x4_f32 v[208:211], v187, v37, v[208:211]
	v_pk_fma_f32 v[240:241], v[112:113], v[204:205], v[240:241] op_sel:[0,1,0] op_sel_hi:[1,1,1]
	s_waitcnt lgkmcnt(4)
	v_pk_fma_f32 v[240:241], v[114:115], v[206:207], v[240:241] op_sel:[0,0,0] op_sel_hi:[1,0,1]
	v_pk_fma_f32 v[240:241], v[116:117], v[206:207], v[240:241] op_sel:[0,1,0] op_sel_hi:[1,1,1]
	v_mfma_f32_16x16x4_f32 v[212:215], v191, v37, v[212:215]
	v_pk_fma_f32 v[242:243], v[118:119], v[204:205], v[242:243] op_sel:[0,0,0] op_sel_hi:[1,0,1]
	v_pk_fma_f32 v[242:243], v[120:121], v[204:205], v[242:243] op_sel:[0,1,0] op_sel_hi:[1,1,1]
	v_pk_fma_f32 v[242:243], v[122:123], v[206:207], v[242:243] op_sel:[0,0,0] op_sel_hi:[1,0,1]
	v_mfma_f32_16x16x4_f32 v[216:219], v195, v37, v[216:219]
	v_pk_fma_f32 v[242:243], v[124:125], v[206:207], v[242:243] op_sel:[0,1,0] op_sel_hi:[1,1,1]
	v_fmac_f32_e32 v241, v126, v240
	v_pk_fma_f32 v[242:243], v[128:129], v[240:241], v[242:243] op_sel:[0,0,0] op_sel_hi:[1,0,1]
	v_mfma_f32_16x16x4_f32 v[220:223], v199, v37, v[220:223]
	v_pk_fma_f32 v[242:243], v[130:131], v[240:241], v[242:243] op_sel:[0,1,0] op_sel_hi:[1,1,1]
	v_fmac_f32_e32 v243, v127, v242
	v_mov_b32_e32 v252, v240
	v_mov_b32_e32 v253, v241
	v_mov_b32_e32 v254, v242
	v_mov_b32_e32 v255, v243
	s_nop 0
	v_permlane32_swap_b32_e32 v252, v254
	v_permlane32_swap_b32_e32 v253, v255
	s_nop 0
	v_mfma_f32_16x16x4_f32 v[248:251], v82, v252, v[240:243]
	v_mfma_f32_16x16x4_f32 v[248:251], v83, v253, v[248:251]
	v_mfma_f32_16x16x4_f32 v[208:211], v184, v252, v[208:211]
	v_mfma_f32_16x16x4_f32 v[212:215], v188, v252, v[212:215]
	v_mfma_f32_16x16x4_f32 v[216:219], v192, v252, v[216:219]
	v_mfma_f32_16x16x4_f32 v[220:223], v196, v252, v[220:223]
	s_mov_b64 exec, s[98:99]
	ds_write_b32 v231, v248
	ds_write_b32 v231, v249 offset:256
	ds_write_b32 v231, v250 offset:512
	ds_write_b32 v231, v251 offset:768
	s_mov_b64 exec, -1
	v_mfma_f32_16x16x4_f32 v[208:211], v185, v253, v[208:211]
	v_mfma_f32_16x16x4_f32 v[212:215], v189, v253, v[212:215]
	v_mfma_f32_16x16x4_f32 v[216:219], v193, v253, v[216:219]
	v_mfma_f32_16x16x4_f32 v[220:223], v197, v253, v[220:223]
	s_waitcnt lgkmcnt(7)
	v_pk_mul_f32 v[208:209], v[208:209], v[88:89]
	v_pk_mul_f32 v[210:211], v[210:211], v[90:91]
	s_nop 0
	v_mfma_f32_16x16x4_f32 v[72:75], v140, v208, v[72:75]
	s_waitcnt lgkmcnt(6)
	v_pk_mul_f32 v[212:213], v[212:213], v[92:93]
	v_mfma_f32_16x16x4_f32 v[244:247], v141, v209, 0
	v_pk_mul_f32 v[214:215], v[214:215], v[94:95]
	v_mfma_f32_16x16x4_f32 v[72:75], v142, v210, v[72:75]
	s_waitcnt lgkmcnt(5)
	v_pk_mul_f32 v[216:217], v[216:217], v[96:97]
	v_mfma_f32_16x16x4_f32 v[244:247], v143, v211, v[244:247]
	v_pk_mul_f32 v[218:219], v[218:219], v[98:99]
	v_mfma_f32_16x16x4_f32 v[72:75], v144, v212, v[72:75]
	s_waitcnt lgkmcnt(4)
	v_pk_mul_f32 v[220:221], v[220:221], v[100:101]
	v_mfma_f32_16x16x4_f32 v[244:247], v145, v213, v[244:247]
	v_pk_mul_f32 v[222:223], v[222:223], v[102:103]
	v_mfma_f32_16x16x4_f32 v[72:75], v146, v214, v[72:75]
	ds_read_b64 v[186:187], v34 offset:9984
	ds_read_b64 v[190:191], v34 offset:11008
	v_mfma_f32_16x16x4_f32 v[244:247], v147, v215, v[244:247]
	ds_read_b64 v[194:195], v34 offset:12032
	ds_read_b64 v[198:199], v34 offset:13056
	v_mfma_f32_16x16x4_f32 v[72:75], v148, v216, v[72:75]
	ds_read_b64 v[184:185], v236 offset:9984
	ds_read_b64 v[188:189], v236 offset:11008
	ds_read_b64 v[80:81], v32
	ds_read_b64 v[82:83], v33
	ds_read_b32 v36, v239 offset:4096
	v_mfma_f32_16x16x4_f32 v[244:247], v149, v217, v[244:247]
	ds_read_b64 v[192:193], v236 offset:12032
	ds_read_b64 v[196:197], v236 offset:13056
	ds_read_b32 v37, v239 offset:4352
	ds_read_b128 v[88:91], v26
	ds_read_b128 v[92:95], v26 offset:1024
	v_mfma_f32_16x16x4_f32 v[72:75], v150, v218, v[72:75]
	ds_read_b128 v[96:99], v26 offset:2048
	ds_read_b128 v[100:103], v26 offset:3072
	ds_read_b32 v104, v29 offset:4
	v_mfma_f32_16x16x4_f32 v[244:247], v151, v219, v[244:247]
	ds_read_b32 v105, v29 offset:76
	ds_read_b64 v[106:107], v29 offset:8
	ds_read_b64 v[108:109], v29 offset:40
	v_mfma_f32_16x16x4_f32 v[72:75], v152, v220, v[72:75]
	ds_read_b32 v126, v31 offset:4
	ds_read_b32 v127, v31 offset:76
	ds_read_b64 v[128:129], v31 offset:8
	v_mfma_f32_16x16x4_f32 v[244:247], v153, v221, v[244:247]
	ds_read_b64 v[130:131], v31 offset:40
	ds_read_b64 v[110:111], v30
	ds_read_b64 v[112:113], v30 offset:32
	v_mfma_f32_16x16x4_f32 v[72:75], v154, v222, v[72:75]
	ds_read_b64 v[114:115], v30 offset:64
	ds_read_b64 v[116:117], v30 offset:96
	ds_read_b64 v[118:119], v30 offset:8
	v_mfma_f32_16x16x4_f32 v[244:247], v155, v223, v[244:247]
	ds_read_b64 v[120:121], v30 offset:40
	ds_read_b64 v[122:123], v30 offset:72
	ds_read_b64 v[124:125], v30 offset:104
	s_waitcnt lgkmcnt(15)
	v_mfma_f32_16x16x4_f32 v[208:211], v186, v38, v[208:211]
	v_mfma_f32_16x16x4_f32 v[212:215], v190, v38, v[212:215]
	v_pk_add_f32 v[72:73], v[72:73], v[244:245]
	v_pk_add_f32 v[74:75], v[74:75], v[246:247]
	v_fmac_f32_e32 v73, v156, v72
	v_mfma_f32_16x16x4_f32 v[216:219], v194, v38, v[216:219]
	v_pk_fma_f32 v[74:75], v[158:159], v[72:73], v[74:75] op_sel:[0,0,0] op_sel_hi:[1,0,1]
	v_pk_fma_f32 v[74:75], v[160:161], v[72:73], v[74:75] op_sel:[0,1,0] op_sel_hi:[1,1,1]
	v_fmac_f32_e32 v75, v157, v74
	v_mfma_f32_16x16x4_f32 v[240:243], v80, v36, 0
	ds_bpermute_b32 v204, v232, v72
	ds_bpermute_b32 v205, v232, v73
	ds_bpermute_b32 v206, v232, v74
	v_mfma_f32_16x16x4_f32 v[240:243], v81, v37, v[240:243]
	ds_bpermute_b32 v207, v232, v75
	ds_read_b128 v[140:143], v226 offset:9984
	ds_read_b128 v[144:147], v226 offset:10048
	v_mfma_f32_16x16x4_f32 v[220:223], v198, v38, v[220:223]
	ds_read_b128 v[148:151], v226 offset:10112
	ds_read_b128 v[152:155], v226 offset:10176
	s_waitcnt lgkmcnt(6)
	v_pk_fma_f32 v[72:73], v[162:163], v[204:205], v[72:73] op_sel:[0,0,0] op_sel_hi:[1,0,1]
	v_mfma_f32_16x16x4_f32 v[208:211], v187, v39, v[208:211]
	v_pk_fma_f32 v[72:73], v[164:165], v[204:205], v[72:73] op_sel:[0,1,0] op_sel_hi:[1,1,1]
	s_waitcnt lgkmcnt(4)
	v_pk_fma_f32 v[72:73], v[166:167], v[206:207], v[72:73] op_sel:[0,0,0] op_sel_hi:[1,0,1]
	v_pk_fma_f32 v[72:73], v[168:169], v[206:207], v[72:73] op_sel:[0,1,0] op_sel_hi:[1,1,1]
	v_mfma_f32_16x16x4_f32 v[212:215], v191, v39, v[212:215]
	v_pk_fma_f32 v[74:75], v[170:171], v[204:205], v[74:75] op_sel:[0,0,0] op_sel_hi:[1,0,1]
	v_pk_fma_f32 v[74:75], v[172:173], v[204:205], v[74:75] op_sel:[0,1,0] op_sel_hi:[1,1,1]
	v_pk_fma_f32 v[74:75], v[174:175], v[206:207], v[74:75] op_sel:[0,0,0] op_sel_hi:[1,0,1]
	v_mfma_f32_16x16x4_f32 v[216:219], v195, v39, v[216:219]
	v_pk_fma_f32 v[74:75], v[176:177], v[206:207], v[74:75] op_sel:[0,1,0] op_sel_hi:[1,1,1]
	v_fmac_f32_e32 v73, v178, v72
	v_pk_fma_f32 v[74:75], v[180:181], v[72:73], v[74:75] op_sel:[0,0,0] op_sel_hi:[1,0,1]
	v_mfma_f32_16x16x4_f32 v[220:223], v199, v39, v[220:223]
	v_pk_fma_f32 v[74:75], v[182:183], v[72:73], v[74:75] op_sel:[0,1,0] op_sel_hi:[1,1,1]
	v_fmac_f32_e32 v75, v179, v74
	v_mov_b32_e32 v252, v72
	v_mov_b32_e32 v253, v73
	v_mov_b32_e32 v254, v74
	v_mov_b32_e32 v255, v75
	s_nop 0
	v_permlane32_swap_b32_e32 v252, v254
	v_permlane32_swap_b32_e32 v253, v255
	s_nop 0
	v_mfma_f32_16x16x4_f32 v[248:251], v134, v252, v[72:75]
	v_mfma_f32_16x16x4_f32 v[248:251], v135, v253, v[248:251]
	v_mfma_f32_16x16x4_f32 v[208:211], v184, v252, v[208:211]
	v_mfma_f32_16x16x4_f32 v[212:215], v188, v252, v[212:215]
	v_mfma_f32_16x16x4_f32 v[216:219], v192, v252, v[216:219]
	v_mfma_f32_16x16x4_f32 v[220:223], v196, v252, v[220:223]
	s_mov_b64 exec, s[98:99]
	ds_write_b32 v231, v248 offset:2048
	ds_write_b32 v231, v249 offset:2304
	ds_write_b32 v231, v250 offset:2560
	ds_write_b32 v231, v251 offset:2816
	s_mov_b64 exec, -1
	v_mfma_f32_16x16x4_f32 v[208:211], v185, v253, v[208:211]
	v_mfma_f32_16x16x4_f32 v[212:215], v189, v253, v[212:215]
	v_mfma_f32_16x16x4_f32 v[216:219], v193, v253, v[216:219]
	v_mfma_f32_16x16x4_f32 v[220:223], v197, v253, v[220:223]
	s_waitcnt lgkmcnt(7)
	v_pk_mul_f32 v[208:209], v[208:209], v[140:141]
	v_pk_mul_f32 v[210:211], v[210:211], v[142:143]
	s_nop 0
	v_mfma_f32_16x16x4_f32 v[240:243], v88, v208, v[240:243]
	s_waitcnt lgkmcnt(6)
	v_pk_mul_f32 v[212:213], v[212:213], v[144:145]
	v_mfma_f32_16x16x4_f32 v[244:247], v89, v209, 0
	v_pk_mul_f32 v[214:215], v[214:215], v[146:147]
	v_mfma_f32_16x16x4_f32 v[240:243], v90, v210, v[240:243]
	s_waitcnt lgkmcnt(5)
	v_pk_mul_f32 v[216:217], v[216:217], v[148:149]
	v_mfma_f32_16x16x4_f32 v[244:247], v91, v211, v[244:247]
	v_pk_mul_f32 v[218:219], v[218:219], v[150:151]
	v_mfma_f32_16x16x4_f32 v[240:243], v92, v212, v[240:243]
	s_waitcnt lgkmcnt(4)
	v_pk_mul_f32 v[220:221], v[220:221], v[152:153]
	v_mfma_f32_16x16x4_f32 v[244:247], v93, v213, v[244:247]
	v_pk_mul_f32 v[222:223], v[222:223], v[154:155]
	v_mfma_f32_16x16x4_f32 v[240:243], v94, v214, v[240:243]
	ds_read_b64 v[186:187], v35
	ds_read_b64 v[190:191], v35 offset:1024
	v_mfma_f32_16x16x4_f32 v[244:247], v95, v215, v[244:247]
	ds_read_b64 v[194:195], v35 offset:2048
	ds_read_b64 v[198:199], v35 offset:3072
	v_mfma_f32_16x16x4_f32 v[240:243], v96, v216, v[240:243]
	ds_read_b64 v[184:185], v27
	ds_read_b64 v[188:189], v27 offset:1024
	ds_read_b64 v[132:133], v32 offset:9984
	ds_read_b64 v[134:135], v33 offset:9984
	ds_read_b32 v38, v239 offset:6144
	v_mfma_f32_16x16x4_f32 v[244:247], v97, v217, v[244:247]
	ds_read_b64 v[192:193], v27 offset:2048
	ds_read_b64 v[196:197], v27 offset:3072
	ds_read_b32 v39, v239 offset:6400
	ds_read_b128 v[140:143], v26 offset:9984
	ds_read_b128 v[144:147], v26 offset:11008
	v_mfma_f32_16x16x4_f32 v[240:243], v98, v218, v[240:243]
	ds_read_b128 v[148:151], v26 offset:12032
	ds_read_b128 v[152:155], v26 offset:13056
	ds_read_b32 v156, v29 offset:9988
	v_mfma_f32_16x16x4_f32 v[244:247], v99, v219, v[244:247]
	ds_read_b32 v157, v29 offset:10060
	ds_read_b64 v[158:159], v29 offset:9992
	ds_read_b64 v[160:161], v29 offset:10024
	v_mfma_f32_16x16x4_f32 v[240:243], v100, v220, v[240:243]
	ds_read_b32 v178, v31 offset:9988
	ds_read_b32 v179, v31 offset:10060
	ds_read_b64 v[180:181], v31 offset:9992
	v_mfma_f32_16x16x4_f32 v[244:247], v101, v221, v[244:247]
	ds_read_b64 v[182:183], v31 offset:10024
	ds_read_b64 v[162:163], v30 offset:9984
	ds_read_b64 v[164:165], v30 offset:10016
	v_mfma_f32_16x16x4_f32 v[240:243], v102, v222, v[240:243]
	ds_read_b64 v[166:167], v30 offset:10048
	ds_read_b64 v[168:169], v30 offset:10080
	ds_read_b64 v[170:171], v30 offset:9992
	v_mfma_f32_16x16x4_f32 v[244:247], v103, v223, v[244:247]
	ds_read_b64 v[172:173], v30 offset:10024
	ds_read_b64 v[174:175], v30 offset:10056
	ds_read_b64 v[176:177], v30 offset:10088
	s_waitcnt lgkmcnt(15)
	v_mfma_f32_16x16x4_f32 v[208:211], v186, v36, v[208:211]
	v_mfma_f32_16x16x4_f32 v[212:215], v190, v36, v[212:215]
	v_pk_add_f32 v[240:241], v[240:241], v[244:245]
	v_pk_add_f32 v[242:243], v[242:243], v[246:247]
	v_fmac_f32_e32 v241, v104, v240
	v_mfma_f32_16x16x4_f32 v[216:219], v194, v36, v[216:219]
	v_pk_fma_f32 v[242:243], v[106:107], v[240:241], v[242:243] op_sel:[0,0,0] op_sel_hi:[1,0,1]
	v_pk_fma_f32 v[242:243], v[108:109], v[240:241], v[242:243] op_sel:[0,1,0] op_sel_hi:[1,1,1]
	v_fmac_f32_e32 v243, v105, v242
	v_mfma_f32_16x16x4_f32 v[72:75], v132, v38, 0
	ds_bpermute_b32 v204, v232, v240
	ds_bpermute_b32 v205, v232, v241
	ds_bpermute_b32 v206, v232, v242
	v_mfma_f32_16x16x4_f32 v[72:75], v133, v39, v[72:75]
	ds_bpermute_b32 v207, v232, v243
	ds_read_b128 v[88:91], v28
	ds_read_b128 v[92:95], v28 offset:64
	v_mfma_f32_16x16x4_f32 v[220:223], v198, v36, v[220:223]
	ds_read_b128 v[96:99], v28 offset:128
	ds_read_b128 v[100:103], v28 offset:192
	s_waitcnt lgkmcnt(6)
	v_pk_fma_f32 v[240:241], v[110:111], v[204:205], v[240:241] op_sel:[0,0,0] op_sel_hi:[1,0,1]
	v_mfma_f32_16x16x4_f32 v[208:211], v187, v37, v[208:211]
	v_pk_fma_f32 v[240:241], v[112:113], v[204:205], v[240:241] op_sel:[0,1,0] op_sel_hi:[1,1,1]
	s_waitcnt lgkmcnt(4)
	v_pk_fma_f32 v[240:241], v[114:115], v[206:207], v[240:241] op_sel:[0,0,0] op_sel_hi:[1,0,1]
	v_pk_fma_f32 v[240:241], v[116:117], v[206:207], v[240:241] op_sel:[0,1,0] op_sel_hi:[1,1,1]
	v_mfma_f32_16x16x4_f32 v[212:215], v191, v37, v[212:215]
	v_pk_fma_f32 v[242:243], v[118:119], v[204:205], v[242:243] op_sel:[0,0,0] op_sel_hi:[1,0,1]
	v_pk_fma_f32 v[242:243], v[120:121], v[204:205], v[242:243] op_sel:[0,1,0] op_sel_hi:[1,1,1]
	v_pk_fma_f32 v[242:243], v[122:123], v[206:207], v[242:243] op_sel:[0,0,0] op_sel_hi:[1,0,1]
	v_mfma_f32_16x16x4_f32 v[216:219], v195, v37, v[216:219]
	v_pk_fma_f32 v[242:243], v[124:125], v[206:207], v[242:243] op_sel:[0,1,0] op_sel_hi:[1,1,1]
	v_fmac_f32_e32 v241, v126, v240
	v_pk_fma_f32 v[242:243], v[128:129], v[240:241], v[242:243] op_sel:[0,0,0] op_sel_hi:[1,0,1]
	v_mfma_f32_16x16x4_f32 v[220:223], v199, v37, v[220:223]
	v_pk_fma_f32 v[242:243], v[130:131], v[240:241], v[242:243] op_sel:[0,1,0] op_sel_hi:[1,1,1]
	v_fmac_f32_e32 v243, v127, v242
	v_mov_b32_e32 v252, v240
	v_mov_b32_e32 v253, v241
	v_mov_b32_e32 v254, v242
	v_mov_b32_e32 v255, v243
	s_nop 0
	v_permlane32_swap_b32_e32 v252, v254
	v_permlane32_swap_b32_e32 v253, v255
	s_nop 0
	v_mfma_f32_16x16x4_f32 v[248:251], v82, v252, v[240:243]
	v_mfma_f32_16x16x4_f32 v[248:251], v83, v253, v[248:251]
	v_mfma_f32_16x16x4_f32 v[208:211], v184, v252, v[208:211]
	v_mfma_f32_16x16x4_f32 v[212:215], v188, v252, v[212:215]
	v_mfma_f32_16x16x4_f32 v[216:219], v192, v252, v[216:219]
	v_mfma_f32_16x16x4_f32 v[220:223], v196, v252, v[220:223]
	s_mov_b64 exec, s[98:99]
	ds_write_b32 v231, v248 offset:4096
	ds_write_b32 v231, v249 offset:4352
	ds_write_b32 v231, v250 offset:4608
	ds_write_b32 v231, v251 offset:4864
	s_mov_b64 exec, -1
	v_mfma_f32_16x16x4_f32 v[208:211], v185, v253, v[208:211]
	v_mfma_f32_16x16x4_f32 v[212:215], v189, v253, v[212:215]
	v_mfma_f32_16x16x4_f32 v[216:219], v193, v253, v[216:219]
	v_mfma_f32_16x16x4_f32 v[220:223], v197, v253, v[220:223]
	s_waitcnt lgkmcnt(7)
	v_pk_mul_f32 v[208:209], v[208:209], v[88:89]
	v_pk_mul_f32 v[210:211], v[210:211], v[90:91]
	s_nop 0
	v_mfma_f32_16x16x4_f32 v[72:75], v140, v208, v[72:75]
	s_waitcnt lgkmcnt(6)
	v_pk_mul_f32 v[212:213], v[212:213], v[92:93]
	v_mfma_f32_16x16x4_f32 v[244:247], v141, v209, 0
	v_pk_mul_f32 v[214:215], v[214:215], v[94:95]
	v_mfma_f32_16x16x4_f32 v[72:75], v142, v210, v[72:75]
	s_waitcnt lgkmcnt(5)
	v_pk_mul_f32 v[216:217], v[216:217], v[96:97]
	v_mfma_f32_16x16x4_f32 v[244:247], v143, v211, v[244:247]
	v_pk_mul_f32 v[218:219], v[218:219], v[98:99]
	v_mfma_f32_16x16x4_f32 v[72:75], v144, v212, v[72:75]
	s_waitcnt lgkmcnt(4)
	v_pk_mul_f32 v[220:221], v[220:221], v[100:101]
	v_mfma_f32_16x16x4_f32 v[244:247], v145, v213, v[244:247]
	v_pk_mul_f32 v[222:223], v[222:223], v[102:103]
	v_mfma_f32_16x16x4_f32 v[72:75], v146, v214, v[72:75]
	ds_read_b64 v[186:187], v35 offset:9984
	ds_read_b64 v[190:191], v35 offset:11008
	v_mfma_f32_16x16x4_f32 v[244:247], v147, v215, v[244:247]
	ds_read_b64 v[194:195], v35 offset:12032
	ds_read_b64 v[198:199], v35 offset:13056
	v_mfma_f32_16x16x4_f32 v[72:75], v148, v216, v[72:75]
	ds_read_b64 v[184:185], v27 offset:9984
	ds_read_b64 v[188:189], v27 offset:11008
	v_mfma_f32_16x16x4_f32 v[244:247], v149, v217, v[244:247]
	ds_read_b64 v[192:193], v27 offset:12032
	ds_read_b64 v[196:197], v27 offset:13056
	v_mfma_f32_16x16x4_f32 v[72:75], v150, v218, v[72:75]
	v_mfma_f32_16x16x4_f32 v[244:247], v151, v219, v[244:247]
	v_mfma_f32_16x16x4_f32 v[72:75], v152, v220, v[72:75]
	v_mfma_f32_16x16x4_f32 v[244:247], v153, v221, v[244:247]
	v_mfma_f32_16x16x4_f32 v[72:75], v154, v222, v[72:75]
	v_mfma_f32_16x16x4_f32 v[244:247], v155, v223, v[244:247]
	s_waitcnt lgkmcnt(7)
	v_mfma_f32_16x16x4_f32 v[208:211], v186, v38, v[208:211]
	s_waitcnt lgkmcnt(6)
	v_mfma_f32_16x16x4_f32 v[212:215], v190, v38, v[212:215]
	v_pk_add_f32 v[72:73], v[72:73], v[244:245]
	v_pk_add_f32 v[74:75], v[74:75], v[246:247]
	v_fmac_f32_e32 v73, v156, v72
	s_waitcnt lgkmcnt(5)
	v_mfma_f32_16x16x4_f32 v[216:219], v194, v38, v[216:219]
	v_pk_fma_f32 v[74:75], v[158:159], v[72:73], v[74:75] op_sel:[0,0,0] op_sel_hi:[1,0,1]
	v_pk_fma_f32 v[74:75], v[160:161], v[72:73], v[74:75] op_sel:[0,1,0] op_sel_hi:[1,1,1]
	v_fmac_f32_e32 v75, v157, v74
	s_waitcnt lgkmcnt(4)
	v_mfma_f32_16x16x4_f32 v[220:223], v198, v38, v[220:223]
	ds_bpermute_b32 v204, v232, v72
	ds_bpermute_b32 v205, v232, v73
	ds_bpermute_b32 v206, v232, v74
	v_mfma_f32_16x16x4_f32 v[208:211], v187, v39, v[208:211]
	ds_bpermute_b32 v207, v232, v75
	ds_read_b128 v[140:143], v28 offset:9984
	ds_read_b128 v[144:147], v28 offset:10048
	v_mfma_f32_16x16x4_f32 v[212:215], v191, v39, v[212:215]
	ds_read_b128 v[148:151], v28 offset:10112
	ds_read_b128 v[152:155], v28 offset:10176
	s_waitcnt lgkmcnt(6)
	v_pk_fma_f32 v[72:73], v[162:163], v[204:205], v[72:73] op_sel:[0,0,0] op_sel_hi:[1,0,1]
	v_mfma_f32_16x16x4_f32 v[216:219], v195, v39, v[216:219]
	v_pk_fma_f32 v[72:73], v[164:165], v[204:205], v[72:73] op_sel:[0,1,0] op_sel_hi:[1,1,1]
	s_waitcnt lgkmcnt(4)
	v_pk_fma_f32 v[72:73], v[166:167], v[206:207], v[72:73] op_sel:[0,0,0] op_sel_hi:[1,0,1]
	v_pk_fma_f32 v[72:73], v[168:169], v[206:207], v[72:73] op_sel:[0,1,0] op_sel_hi:[1,1,1]
	v_mfma_f32_16x16x4_f32 v[220:223], v199, v39, v[220:223]
	v_pk_fma_f32 v[74:75], v[170:171], v[204:205], v[74:75] op_sel:[0,0,0] op_sel_hi:[1,0,1]
	v_pk_fma_f32 v[74:75], v[172:173], v[204:205], v[74:75] op_sel:[0,1,0] op_sel_hi:[1,1,1]
	v_pk_fma_f32 v[74:75], v[174:175], v[206:207], v[74:75] op_sel:[0,0,0] op_sel_hi:[1,0,1]
	v_pk_fma_f32 v[74:75], v[176:177], v[206:207], v[74:75] op_sel:[0,1,0] op_sel_hi:[1,1,1]
	v_fmac_f32_e32 v73, v178, v72
	v_pk_fma_f32 v[74:75], v[180:181], v[72:73], v[74:75] op_sel:[0,0,0] op_sel_hi:[1,0,1]
	v_pk_fma_f32 v[74:75], v[182:183], v[72:73], v[74:75] op_sel:[0,1,0] op_sel_hi:[1,1,1]
	v_fmac_f32_e32 v75, v179, v74
	v_mov_b32_e32 v252, v72
	v_mov_b32_e32 v253, v73
	v_mov_b32_e32 v254, v74
	v_mov_b32_e32 v255, v75
	s_nop 0
	v_permlane32_swap_b32_e32 v252, v254
	v_permlane32_swap_b32_e32 v253, v255
	s_nop 0
	v_mfma_f32_16x16x4_f32 v[248:251], v134, v252, v[72:75]
	v_mfma_f32_16x16x4_f32 v[248:251], v135, v253, v[248:251]
	v_mfma_f32_16x16x4_f32 v[208:211], v184, v252, v[208:211]
	v_mfma_f32_16x16x4_f32 v[212:215], v188, v252, v[212:215]
	v_mfma_f32_16x16x4_f32 v[216:219], v192, v252, v[216:219]
	v_mfma_f32_16x16x4_f32 v[220:223], v196, v252, v[220:223]
	s_mov_b64 exec, s[98:99]
	ds_write_b32 v231, v248 offset:6144
	ds_write_b32 v231, v249 offset:6400
	ds_write_b32 v231, v250 offset:6656
	ds_write_b32 v231, v251 offset:6912
	s_mov_b64 exec, -1
	v_mfma_f32_16x16x4_f32 v[208:211], v185, v253, v[208:211]
	v_mfma_f32_16x16x4_f32 v[212:215], v189, v253, v[212:215]
	v_mfma_f32_16x16x4_f32 v[216:219], v193, v253, v[216:219]
	v_mfma_f32_16x16x4_f32 v[220:223], v197, v253, v[220:223]
	s_waitcnt lgkmcnt(7)
	v_pk_mul_f32 v[208:209], v[208:209], v[140:141]
	v_pk_mul_f32 v[210:211], v[210:211], v[142:143]
	s_waitcnt lgkmcnt(6)
	v_pk_mul_f32 v[212:213], v[212:213], v[144:145]
	v_pk_mul_f32 v[214:215], v[214:215], v[146:147]
	s_waitcnt lgkmcnt(5)
	v_pk_mul_f32 v[216:217], v[216:217], v[148:149]
	v_pk_mul_f32 v[218:219], v[218:219], v[150:151]
	s_waitcnt lgkmcnt(4)
	s_nop 3
	v_pk_mul_f32 v[220:221], v[220:221], v[152:153]
	v_pk_mul_f32 v[222:223], v[222:223], v[154:155]
	s_branch .LBB0_655

.Lmy_ck_drE_h:
	s_waitcnt lgkmcnt(0)
	s_bfe_u32 s96, s62, 0x20006
	s_and_b32 s97, s96, 1
	s_mul_i32 s97, s97, 0x2700
	s_mov_b32 s101, 0x1c000
	s_mov_b32 s100, 0x6100
	s_bitcmp0_b32 s65, 0
	s_cselect_b32 s101, 0xe000, s101
	s_cselect_b32 s100, 0x4e00, s100
	s_cmp_gt_u32 s96, 1
	s_cselect_b32 s100, s100, 0
	s_add_i32 s97, s97, s101
	s_add_i32 s97, s97, s100
	s_mov_b32 s96, s97
	v_and_b32_e32 v72, 3, v233
	v_lshrrev_b32_e32 v73, 2, v233
	v_lshlrev_b32_e32 v72, 2, v72
	v_lshl_add_u32 v72, v73, 8, v72
	v_lshl_add_u32 v72, v234, 6, v72
	s_add_i32 s97, s96, 0x1000
	v_add_u32_e32 v78, s97, v72
	v_xor_b32_e32 v79, v224, v234
	v_lshl_add_u32 v79, v79, 4, s96
	ds_read_b128 v[96:99], v79
	ds_read_b128 v[100:103], v79 offset:1024
	ds_read_b128 v[104:107], v79 offset:2048
	ds_read_b128 v[108:111], v79 offset:3072
	ds_read_b32 v80, v78
	ds_read_b32 v81, v78 offset:16
	ds_read_b32 v82, v78 offset:32
	ds_read_b32 v83, v78 offset:48
	ds_read_b32 v84, v78 offset:1024
	ds_read_b32 v85, v78 offset:1040
	ds_read_b32 v86, v78 offset:1056
	ds_read_b32 v87, v78 offset:1072
	ds_read_b32 v88, v78 offset:2048
	ds_read_b32 v89, v78 offset:2064
	ds_read_b32 v90, v78 offset:2080
	ds_read_b32 v91, v78 offset:2096
	ds_read_b32 v92, v78 offset:3072
	ds_read_b32 v93, v78 offset:3088
	ds_read_b32 v94, v78 offset:3104
	ds_read_b32 v95, v78 offset:3120
	v_lshl_add_u32 v74, v224, 2, s96
	ds_write_b32 v74, v235 offset:9728
	v_add_u32_e32 v75, -1, v233
	v_mov_b32_e32 v76, -1
	v_cndmask_b32_e64 v75, v76, v75, s[98:99]
	v_cmp_lt_u32_e64 s[100:101], 7, v233
	v_add_u32_e32 v76, -8, v233
	v_and_b32_e32 v77, 1, v234
	v_cndmask_b32_e64 v75, v75, v76, s[100:101]
	v_lshlrev_b32_e32 v77, 2, v77
	v_sub_u32_e32 v76, v75, v77
	v_lshlrev_b32_e32 v77, 2, v234
	v_sub_u32_e32 v77, v233, v77
	v_add_u32_e32 v77, -1, v77
	s_waitcnt lgkmcnt(15)
	v_mfma_f32_16x16x4_f32 v[244:247], v80, v96, 0
	v_mfma_f32_16x16x4_f32 v[240:243], v81, v97, 0
	s_waitcnt lgkmcnt(14)
	v_mfma_f32_16x16x4_f32 v[244:247], v82, v98, v[244:247]
	s_waitcnt lgkmcnt(13)
	v_mfma_f32_16x16x4_f32 v[240:243], v83, v99, v[240:243]
	s_waitcnt lgkmcnt(12)
	v_mfma_f32_16x16x4_f32 v[244:247], v84, v100, v[244:247]
	s_waitcnt lgkmcnt(11)
	v_mfma_f32_16x16x4_f32 v[240:243], v85, v101, v[240:243]
	s_waitcnt lgkmcnt(10)
	v_mfma_f32_16x16x4_f32 v[244:247], v86, v102, v[244:247]
	s_waitcnt lgkmcnt(9)
	v_mfma_f32_16x16x4_f32 v[240:243], v87, v103, v[240:243]
	s_waitcnt lgkmcnt(8)
	v_mfma_f32_16x16x4_f32 v[244:247], v88, v104, v[244:247]
	s_waitcnt lgkmcnt(7)
	v_mfma_f32_16x16x4_f32 v[240:243], v89, v105, v[240:243]
	s_waitcnt lgkmcnt(6)
	v_mfma_f32_16x16x4_f32 v[244:247], v90, v106, v[244:247]
	s_waitcnt lgkmcnt(5)
	v_mfma_f32_16x16x4_f32 v[240:243], v91, v107, v[240:243]
	s_waitcnt lgkmcnt(4)
	v_mfma_f32_16x16x4_f32 v[244:247], v92, v108, v[244:247]
	s_waitcnt lgkmcnt(3)
	v_mfma_f32_16x16x4_f32 v[240:243], v93, v109, v[240:243]
	s_waitcnt lgkmcnt(2)
	v_mfma_f32_16x16x4_f32 v[244:247], v94, v110, v[244:247]
	s_waitcnt lgkmcnt(1)
	v_mfma_f32_16x16x4_f32 v[240:243], v95, v111, v[240:243]
	s_nop 9
	v_add_f32_e32 v244, v244, v240
	v_add_f32_e32 v245, v245, v241
	v_add_f32_e32 v246, v246, v242
	v_add_f32_e32 v247, v247, v243
	v_cmp_le_i32_e64 s[96:97], 0, v76
	v_cmp_le_i32_e64 s[100:101], 1, v76
	s_nop 0
	v_cndmask_b32_e64 v128, 0, v244, s[96:97]
	v_cndmask_b32_e64 v129, 0, v245, s[100:101]
	v_cmp_le_i32_e64 s[96:97], 2, v76
	v_cmp_le_i32_e64 s[100:101], 3, v76
	s_nop 0
	v_cndmask_b32_e64 v130, 0, v246, s[96:97]
	v_cndmask_b32_e64 v131, 0, v247, s[100:101]
	s_bfe_u32 s96, s62, 0x20006
	s_and_b32 s97, s96, 1
	s_mul_i32 s97, s97, 0x2700
	s_mov_b32 s101, 0x1c000
	s_mov_b32 s100, 0x6100
	s_bitcmp0_b32 s65, 0
	s_cselect_b32 s101, 0xe000, s101
	s_cselect_b32 s100, 0x4e00, s100
	s_cmp_gt_u32 s96, 1
	s_cselect_b32 s100, s100, 0
	s_add_i32 s97, s97, s101
	s_add_i32 s97, s97, s100
	v_xor_b32_e32 v74, v224, v234
	v_lshl_add_u32 v74, v74, 4, s97
	ds_write_b128 v74, v[128:131] offset:8448
	v_lshlrev_b32_e32 v75, 7, v234
	v_lshl_add_u32 v75, v233, 2, v75
	v_add_u32_e32 v75, s97, v75
	v_cmp_le_i32_e64 s[96:97], 0, v77
	v_cmp_le_i32_e64 s[100:101], 1, v77
	s_nop 0
	v_cndmask_b32_e64 v132, 0, v244, s[96:97]
	v_cndmask_b32_e64 v133, 0, v245, s[100:101]
	v_cmp_le_i32_e64 s[96:97], 2, v77
	v_cmp_le_i32_e64 s[100:101], 3, v77
	s_nop 0
	v_cndmask_b32_e64 v134, 0, v246, s[96:97]
	v_cndmask_b32_e64 v135, 0, v247, s[100:101]
	s_mov_b64 exec, 0x00ff00ff
	ds_write_b32 v75, v132 offset:9472
	ds_write_b32 v75, v133 offset:9504
	ds_write_b32 v75, v134 offset:9536
	ds_write_b32 v75, v135 offset:9568
	s_mov_b64 exec, -1
	s_setprio 0
	s_branch .LBB0_655
	s_nop 0
	s_nop 0
	s_nop 0
	s_nop 0
	s_nop 0
	s_nop 0
	s_nop 0
	s_nop 0
	s_nop 0
	s_nop 0
	s_nop 0
	s_nop 0
	s_nop 0
	s_nop 0
	s_nop 0
	s_nop 0
	s_nop 0
	s_nop 0
	s_nop 0
	s_nop 0
	s_nop 0
	s_nop 0
	s_nop 0
	s_nop 0
	s_nop 0
	s_nop 0
	s_nop 0
	s_nop 0
	s_nop 0
	s_nop 0
	s_nop 0
	s_nop 0
	s_nop 0
	s_nop 0
	s_nop 0
	s_nop 0
	s_nop 0
	s_nop 0
	s_nop 0
	s_nop 0
	s_nop 0
	s_nop 0
	s_nop 0
	s_nop 0
	s_nop 0
	s_nop 0
